# FFT stage-1 units run as a per-class burst between attention units before grid barrier 3 (P3 split in two parts)
# speedup vs baseline: 1.1591x; 1.0174x over previous
.LBB0_233:
	s_or_b64 exec, exec, s[0:1]
	s_cmpk_gt_i32 s10, 0x17ff
	v_lshlrev_b32_e32 v196, 3, v197
	v_lshlrev_b32_e32 v194, 4, v190
	s_waitcnt lgkmcnt(0)
	s_barrier
	s_cbranch_scc1 .LBB0_244
	s_mov_b32 s98, 0
	s_cmpk_lg_i32 s68, 0x100
	s_cbranch_scc1 .Lp2_entry
	s_mov_b32 s86, s11
	s_mov_b32 s87, s64
	s_mov_b32 s88, s76
	s_mov_b32 s89, s77
	s_mov_b64 s[90:91], s[20:21]
	s_mov_b64 s[92:93], s[22:23]
	s_mov_b64 s[94:95], s[26:27]
	s_and_b32 s45, s75, 3
	s_mov_b32 s44, 0
	s_mov_b32 s98, 2
	s_cmp_eq_u32 s45, 0
	s_cbranch_scc1 .Lp2_entry
	s_mov_b32 s98, 1
	s_branch .Lp3_enter
.Lp2_entry:
	v_and_b32_e32 v0, 16, v191
	v_cmp_eq_u32_e64 s[2:3], 0, v0
	v_sub_u32_e32 v0, v189, v196
	v_mov_b32_e32 v1, 0x3f80
	v_cmp_eq_u32_e32 vcc, v189, v196
	v_mov_b32_e32 v199, 0
	s_lshl_b32 s0, s74, 14
	v_cndmask_b32_e32 v2, 0, v1, vcc
	v_cmp_eq_u32_e32 vcc, 1, v0
	s_add_i32 s0, s0, 0
	v_readlane_b32 s4, v254, 27
	v_cndmask_b32_e64 v3, 0, 1.0, vcc
	v_cmp_eq_u32_e32 vcc, 2, v0
	v_or_b32_e32 v160, v3, v2
	v_mov_b32_e32 v195, v199
	v_cndmask_b32_e32 v2, 0, v1, vcc
	v_cmp_eq_u32_e32 vcc, 3, v0
	s_bfe_u32 s18, s4, 0x10006
	s_mov_b64 s[4:5], 0x800
	v_cndmask_b32_e64 v3, 0, 1.0, vcc
	v_cmp_eq_u32_e32 vcc, 4, v0
	v_or_b32_e32 v161, v2, v3
	s_mov_b32 s1, 0
	v_cndmask_b32_e32 v2, 0, v1, vcc
	v_cmp_eq_u32_e32 vcc, 5, v0
	v_or_b32_e32 v221, 6, v197
	v_or_b32_e32 v223, 4, v197
	v_cndmask_b32_e64 v3, 0, 1.0, vcc
	v_cmp_eq_u32_e32 vcc, 6, v0
	v_or_b32_e32 v162, v2, v3
	v_or_b32_e32 v224, 2, v197
	v_cndmask_b32_e32 v2, 0, v1, vcc
	v_cmp_eq_u32_e32 vcc, 7, v0
	s_movk_i32 s19, 0x1000
	v_lshlrev_b32_e32 v202, 1, v196
	v_cndmask_b32_e64 v0, 0, 1.0, vcc
	v_or_b32_e32 v163, v2, v0
	v_or_b32_e32 v0, 16, v196
	v_sub_u32_e32 v2, v189, v0
	v_cmp_eq_u32_e32 vcc, v189, v0
	v_mov_b32_e32 v203, v199
	v_lshlrev_b32_e32 v204, 1, v188
	v_cndmask_b32_e32 v0, 0, v1, vcc
	v_cmp_eq_u32_e32 vcc, 1, v2
	v_mov_b32_e32 v205, v199
	s_mov_b32 s24, s10
	v_cndmask_b32_e64 v3, 0, 1.0, vcc
	v_cmp_eq_u32_e32 vcc, 2, v2
	v_or_b32_e32 v164, v3, v0
	s_nop 0
	v_cndmask_b32_e32 v0, 0, v1, vcc
	v_cmp_eq_u32_e32 vcc, 3, v2
	s_nop 1
	v_cndmask_b32_e64 v3, 0, 1.0, vcc
	v_cmp_eq_u32_e32 vcc, 4, v2
	v_or_b32_e32 v165, v0, v3
	s_nop 0
	v_cndmask_b32_e32 v0, 0, v1, vcc
	v_cmp_eq_u32_e32 vcc, 5, v2
	s_nop 1
	v_cndmask_b32_e64 v3, 0, 1.0, vcc
	v_cmp_eq_u32_e32 vcc, 6, v2
	v_or_b32_e32 v166, v0, v3
	s_nop 0
	v_cndmask_b32_e32 v0, 0, v1, vcc
	v_cmp_eq_u32_e32 vcc, 7, v2
	v_lshl_add_u32 v2, v189, 8, s0
	s_nop 0
	v_cndmask_b32_e64 v1, 0, 1.0, vcc
	v_or_b32_e32 v167, v0, v1
	v_xor_b32_e32 v0, v197, v189
	v_lshlrev_b32_e32 v3, 3, v0
	v_bitop3_b32 v0, v197, v189, 16 bitop3:0x36
	v_lshlrev_b32_e32 v4, 3, v0
	v_bitop3_b32 v0, v197, v189, 2 bitop3:0x36
	v_lshlrev_b32_e32 v5, 3, v0
	v_bitop3_b32 v0, v197, v189, 18 bitop3:0x36
	v_lshlrev_b32_e32 v6, 3, v0
	v_bitop3_b32 v0, v197, v189, 4 bitop3:0x36
	v_lshlrev_b32_e32 v7, 3, v0
	v_bitop3_b32 v0, v197, v189, 20 bitop3:0x36
	v_lshlrev_b32_e32 v8, 3, v0
	v_bitop3_b32 v0, v197, v189, 6 bitop3:0x36
	v_lshlrev_b32_e32 v9, 3, v0
	v_bitop3_b32 v0, v197, v189, 22 bitop3:0x36
	v_lshlrev_b32_e32 v10, 3, v0
	v_bitop3_b32 v0, v197, v189, 8 bitop3:0x36
	v_lshlrev_b32_e32 v11, 3, v0
	v_bitop3_b32 v0, v197, v189, 24 bitop3:0x36
	v_lshlrev_b32_e32 v12, 3, v0
	v_bitop3_b32 v0, v197, v189, 10 bitop3:0x36
	v_lshlrev_b32_e32 v13, 3, v0
	v_bitop3_b32 v0, v197, v189, 26 bitop3:0x36
	v_lshlrev_b32_e32 v14, 3, v0
	v_bitop3_b32 v0, v197, v189, 12 bitop3:0x36
	v_lshlrev_b32_e32 v15, 3, v0
	v_bitop3_b32 v0, v197, v189, 28 bitop3:0x36
	v_lshlrev_b32_e32 v16, 3, v0
	v_bitop3_b32 v0, v197, v189, 14 bitop3:0x36
	v_lshlrev_b32_e32 v17, 3, v0
	v_bitop3_b32 v0, v197, v189, 30 bitop3:0x36
	v_lshlrev_b32_e32 v18, 3, v0
	v_and_b32_e32 v0, 0x300, v194
	v_add_u32_e32 v222, s0, v0
	v_lshl_add_u64 v[0:1], s[42:43], 0, v[194:195]
	v_lshl_add_u64 v[200:201], v[0:1], 0, s[4:5]
	v_add_u32_e32 v195, v2, v3
	v_add_u32_e32 v225, v2, v4
	v_add_u32_e32 v226, v2, v5
	v_add_u32_e32 v227, v2, v6
	v_add_u32_e32 v228, v2, v7
	v_add_u32_e32 v229, v2, v8
	v_add_u32_e32 v230, v2, v9
	v_add_u32_e32 v231, v2, v10
	v_add_u32_e32 v232, v2, v11
	v_add_u32_e32 v233, v2, v12
	v_add_u32_e32 v234, v2, v13
	v_add_u32_e32 v235, v2, v14
	v_add_u32_e32 v236, v2, v15
	v_add_u32_e32 v237, v2, v16
	v_add_u32_e32 v238, v2, v17
	v_add_u32_e32 v239, v2, v18
	s_mov_b64 s[4:5], 0x1000

.LBB0_244:
	s_cmp_eq_u32 s98, 2
	s_cbranch_scc1 .Lp3_enter
	s_waitcnt vmcnt(0)
	s_barrier
	s_mov_b64 s[0:1], exec
	v_readlane_b32 s2, v254, 1
	v_readlane_b32 s3, v254, 2
	v_readlane_b32 s70, v254, 7
	v_readlane_b32 s62, v254, 16
	v_readlane_b32 s64, v254, 18
	v_readlane_b32 s76, v254, 24
	s_and_b64 s[2:3], s[0:1], s[2:3]
	v_readlane_b32 s71, v254, 8
	v_readlane_b32 s63, v254, 17
	v_readlane_b32 s65, v254, 19
	v_readlane_b32 s72, v254, 20
	v_readlane_b32 s73, v254, 21
	v_readlane_b32 s77, v254, 25
	s_mov_b64 exec, s[2:3]
	s_cbranch_execz .LBB0_296
	s_add_i32 s2, 0, 0x20000
	v_mov_b32_e32 v0, s2
	s_waitcnt vmcnt(0) expcnt(0) lgkmcnt(0)
	ds_read_b32 v2, v0
	s_add_i32 s2, 0, 0x20004
	v_mov_b32_e32 v0, s2
	ds_read_b32 v0, v0
	s_waitcnt lgkmcnt(1)
	v_cmp_ne_u32_e32 vcc, 0, v2
	s_cbranch_vccnz .LBB0_260
	v_readlane_b32 s2, v254, 0
	s_mul_i32 s11, s69, s2
	s_add_u32 s2, s42, 0x60d0200
	s_addc_u32 s3, s43, 0
	s_add_u32 s4, s42, 0x60d0400
	s_addc_u32 s5, s43, 0
	s_add_u32 s6, s42, 0x60d0500
	s_addc_u32 s7, s43, 0
	s_add_u32 s8, s42, 0x60d0600
	s_addc_u32 s9, s43, 0
	s_add_u32 s16, s42, 0x60d0700
	s_addc_u32 s17, s43, 0
	s_add_u32 s18, s42, 0x60d0800
	s_addc_u32 s19, s43, 0
	s_add_u32 s24, s42, 0x60d0900
	s_addc_u32 s25, s43, 0
	s_add_u32 s28, s42, 0x60d0a00
	s_addc_u32 s29, s43, 0
	s_add_u32 s30, s42, 0x60d0b00
	s_addc_u32 s31, s43, 0
	s_add_u32 s34, s42, 0x60d0c00
	s_addc_u32 s35, s43, 0
	s_add_u32 s36, s42, 0x60d0d00
	s_addc_u32 s37, s43, 0
	s_add_u32 s44, s42, 0x60d0e00
	s_addc_u32 s45, s43, 0
	s_add_u32 s46, s42, 0x60d0f00
	s_addc_u32 s47, s43, 0
	s_add_u32 s48, s42, 0x60d1000
	s_addc_u32 s49, s43, 0
	s_add_u32 s50, s42, 0x60d1100
	s_addc_u32 s51, s43, 0
	s_add_u32 s52, s42, 0x60d1200
	s_addc_u32 s53, s43, 0
	s_add_u32 s54, s42, 0x60d1300
	s_mul_i32 s11, s11, s68
	s_addc_u32 s55, s43, 0
	s_mov_b32 s33, 1
	v_mov_b32_e32 v16, 0
	s_branch .LBB0_248

.Lp3_pre:
	global_load_dword v1, v0, s[20:21]
	global_load_dword v2, v0, s[22:23]
	v_mbcnt_hi_u32_b32 v0, -1, v218
	v_and_b32_e32 v3, 64, v0
	v_xor_b32_e32 v4, 1, v0
	v_add_u32_e32 v3, 64, v3
	v_cmp_lt_i32_e32 vcc, v4, v3
	v_xor_b32_e32 v5, 2, v0
	v_xor_b32_e32 v6, 4, v0
	v_cndmask_b32_e32 v4, v0, v4, vcc
	v_lshlrev_b32_e32 v142, 2, v4
	v_cmp_lt_i32_e32 vcc, v5, v3
	v_xor_b32_e32 v7, 8, v0
	v_xor_b32_e32 v8, 16, v0
	v_cndmask_b32_e32 v5, v0, v5, vcc
	v_lshlrev_b32_e32 v143, 2, v5
	v_cmp_lt_i32_e32 vcc, v6, v3
	v_xor_b32_e32 v9, 32, v0
	s_add_u32 s0, s42, 0x11800000
	v_cndmask_b32_e32 v6, v0, v6, vcc
	v_lshlrev_b32_e32 v144, 2, v6
	v_cmp_lt_i32_e32 vcc, v7, v3
	s_addc_u32 s1, s43, 0
	v_mov_b32_e32 v99, 0
	v_cndmask_b32_e32 v6, v0, v7, vcc
	v_lshlrev_b32_e32 v145, 2, v6
	v_cmp_lt_i32_e32 vcc, v8, v3
	s_mov_b32 s17, 0
	s_cmpk_lt_i32 s75, 0xc00
	v_cndmask_b32_e32 v6, v0, v8, vcc
	v_lshlrev_b32_e32 v146, 2, v6
	v_cmp_lt_i32_e32 vcc, v9, v3
	s_waitcnt vmcnt(1)
	v_and_b32_e32 v4, 0x7fffffff, v1
	s_waitcnt vmcnt(0)
	v_and_b32_e32 v10, 0x7fffffff, v2
	ds_bpermute_b32 v4, v142, v4
	ds_bpermute_b32 v10, v142, v10
	v_max_f32_e64 v1, |v1|, |v1|
	v_max_f32_e64 v2, |v2|, |v2|
	v_cndmask_b32_e32 v0, v0, v9, vcc
	s_waitcnt lgkmcnt(1)
	v_max_f32_e32 v4, v4, v4
	s_waitcnt lgkmcnt(0)
	v_max_f32_e32 v5, v10, v10
	v_max_f32_e32 v1, v1, v4
	v_max_f32_e32 v2, v2, v5
	ds_bpermute_b32 v4, v143, v1
	ds_bpermute_b32 v5, v143, v2
	v_lshlrev_b32_e32 v147, 2, v0
	s_waitcnt lgkmcnt(1)
	v_max_f32_e32 v4, v4, v4
	s_waitcnt lgkmcnt(0)
	v_max_f32_e32 v5, v5, v5
	v_max_f32_e32 v1, v1, v4
	v_max_f32_e32 v2, v2, v5
	ds_bpermute_b32 v4, v144, v1
	ds_bpermute_b32 v5, v144, v2
	s_waitcnt lgkmcnt(1)
	v_max_f32_e32 v4, v4, v4
	s_waitcnt lgkmcnt(0)
	v_max_f32_e32 v5, v5, v5
	v_max_f32_e32 v1, v1, v4
	v_max_f32_e32 v2, v2, v5
	ds_bpermute_b32 v4, v145, v1
	ds_bpermute_b32 v5, v145, v2
	s_waitcnt lgkmcnt(1)
	v_max_f32_e32 v4, v4, v4
	s_waitcnt lgkmcnt(0)
	v_max_f32_e32 v5, v5, v5
	v_max_f32_e32 v1, v1, v4
	v_max_f32_e32 v2, v2, v5
	ds_bpermute_b32 v4, v146, v1
	ds_bpermute_b32 v5, v146, v2
	s_waitcnt lgkmcnt(1)
	v_max_f32_e32 v0, v4, v4
	s_waitcnt lgkmcnt(0)
	v_max_f32_e32 v3, v5, v5
	v_max_f32_e32 v0, v1, v0
	v_max_f32_e32 v1, v2, v3
	ds_bpermute_b32 v2, v147, v0
	ds_bpermute_b32 v3, v147, v1
	s_waitcnt lgkmcnt(1)
	v_max_f32_e32 v2, v2, v2
	s_waitcnt lgkmcnt(0)
	v_max_f32_e32 v3, v3, v3
	v_max_f32_e32 v0, v0, v2
	v_max_f32_e32 v1, v1, v3
	v_mul_f32_e32 v0, 0x4138aa3b, v0
	v_mul_f32_e32 v0, v0, v1
	s_nop 0
	v_readfirstlane_b32 s2, v0
	s_cbranch_scc0 .LBB0_320
	v_mov_b32_e32 v0, 0x42200000
	s_lshl_b32 s4, s74, 12
	v_lshrrev_b32_e32 v148, 3, v191
	v_cmp_nlt_f32_e64 s[2:3], s2, v0
	s_lshl_b32 s18, s74, 5
	s_add_i32 s4, s4, 0
	s_mov_b32 s19, s17
	v_xor_b32_e32 v0, v148, v191
	s_add_i32 s11, s4, 0x10000
	s_lshl_b64 s[4:5], s[18:19], 2
	v_lshlrev_b32_e32 v0, 4, v0
	s_add_u32 s4, s26, s4
	v_and_b32_e32 v0, 48, v0
	v_lshlrev_b32_e32 v2, 7, v148
	v_xor_b32_e32 v3, v212, v191
	s_movk_i32 s6, 0x70
	s_addc_u32 s5, s27, s5
	v_lshlrev_b32_e32 v98, 4, v197
	v_add_u32_e32 v4, s11, v0
	v_and_b32_e32 v0, 4, v191
	v_and_or_b32 v2, v3, s6, v2
	v_bfe_u32 v3, v191, 1, 3
	v_bitop3_b32 v14, v197, v219, 7 bitop3:0x78
	v_lshl_add_u64 v[100:101], s[4:5], 0, v[98:99]
	v_cmp_eq_u32_e64 s[4:5], 0, v0
	v_and_b32_e32 v0, 56, v220
	v_readlane_b32 s8, v254, 22
	v_lshlrev_b32_e32 v156, 4, v14
	v_bitop3_b32 v14, v197, v3, 2 bitop3:0x36
	v_add_u32_e32 v150, 0, v2
	v_lshlrev_b32_e32 v2, 7, v189
	v_lshlrev_b32_e32 v98, 1, v0
	v_readlane_b32 s9, v254, 23
	v_lshlrev_b32_e32 v157, 4, v14
	v_bitop3_b32 v14, v197, v3, 4 bitop3:0x36
	v_bitop3_b32 v3, v197, v3, 6 bitop3:0x36
	v_add_u32_e32 v151, 0, v2
	v_add_u32_e32 v5, s11, v2
	v_and_b32_e32 v2, 15, v191
	v_lshl_add_u64 v[102:103], s[8:9], 0, v[98:99]
	v_readlane_b32 s8, v254, 5
	v_lshlrev_b32_e32 v159, 4, v3
	v_bitop3_b32 v3, v197, v191, 15 bitop3:0x78
	v_mov_b32_e32 v195, v99
	v_readlane_b32 s9, v254, 6
	v_lshlrev_b32_e32 v158, 4, v14
	v_lshlrev_b32_e32 v14, 3, v3
	v_bitop3_b32 v3, v197, v2, 2 bitop3:0x36
	v_lshl_add_u64 v[106:107], s[8:9], 0, v[194:195]
	s_mov_b64 s[8:9], 0x1000
	v_lshlrev_b32_e32 v15, 3, v3
	v_bitop3_b32 v3, v197, v2, 4 bitop3:0x36
	v_lshl_add_u64 v[108:109], v[106:107], 0, s[8:9]
	s_mov_b64 s[8:9], 0x1400
	v_lshlrev_b32_e32 v16, 3, v3
	v_bitop3_b32 v3, v197, v2, 6 bitop3:0x36
	v_lshl_add_u64 v[110:111], v[106:107], 0, s[8:9]
	s_mov_b64 s[8:9], 0x1800
	v_lshlrev_b32_e32 v17, 3, v3
	v_bitop3_b32 v3, v197, v2, 8 bitop3:0x36
	v_lshl_add_u64 v[112:113], v[106:107], 0, s[8:9]
	s_mov_b64 s[8:9], 0x1c00
	v_lshlrev_b32_e32 v18, 3, v3
	v_bitop3_b32 v3, v197, v2, 10 bitop3:0x36
	v_lshrrev_b32_e32 v152, 3, v190
	v_lshl_add_u64 v[114:115], v[106:107], 0, s[8:9]
	s_mov_b64 s[8:9], 0x2000
	v_lshlrev_b32_e32 v19, 3, v3
	v_bitop3_b32 v3, v197, v2, 12 bitop3:0x36
	v_bitop3_b32 v2, v197, v2, 14 bitop3:0x36
	v_lshl_add_u64 v[116:117], v[106:107], 0, s[8:9]
	s_mov_b64 s[8:9], 0x2400
	v_lshlrev_b32_e32 v21, 3, v2
	v_and_b32_e32 v2, 0x70, v212
	v_or_b32_e32 v160, 8, v152
	v_lshl_add_u64 v[118:119], v[106:107], 0, s[8:9]
	s_mov_b64 s[8:9], 0x2800
	v_bitop3_b32 v23, v191, v2, 48 bitop3:0x6c
	v_lshrrev_b32_e32 v2, 1, v160
	v_lshl_add_u64 v[120:121], v[106:107], 0, s[8:9]
	s_mov_b64 s[8:9], 0x2c00
	v_xor_b32_e32 v2, v2, v191
	v_lshl_add_u64 v[122:123], v[106:107], 0, s[8:9]
	s_mov_b64 s[8:9], 0x3000
	v_lshlrev_b32_e32 v2, 4, v2
	v_or_b32_e32 v162, 24, v152
	v_lshl_add_u64 v[124:125], v[106:107], 0, s[8:9]
	s_mov_b64 s[8:9], 0x3400
	v_and_b32_e32 v25, 0x70, v2
	v_lshrrev_b32_e32 v2, 1, v162
	v_lshl_add_u64 v[126:127], v[106:107], 0, s[8:9]
	s_mov_b64 s[8:9], 0x3800
	v_xor_b32_e32 v2, v2, v191
	v_and_b32_e32 v6, 8, v191
	v_lshl_add_u64 v[104:105], s[0:1], 0, v[98:99]
	v_lshl_add_u64 v[128:129], v[106:107], 0, s[8:9]
	s_mov_b64 s[8:9], 0x3c00
	v_lshlrev_b32_e32 v2, 4, v2
	v_lshlrev_b32_e32 v98, 4, v217
	v_cmp_eq_u32_e64 s[6:7], 0, v6
	v_lshl_add_u64 v[130:131], v[106:107], 0, s[8:9]
	v_bitop3_b32 v6, v197, v191, 7 bitop3:0x78
	v_bitop3_b32 v7, v197, v217, 2 bitop3:0x36
	v_bitop3_b32 v8, v197, v217, 4 bitop3:0x36
	v_bitop3_b32 v9, v197, v217, 6 bitop3:0x36
	v_or_b32_e32 v153, 16, v193
	v_or_b32_e32 v154, 32, v193
	v_or_b32_e32 v155, 48, v193
	v_lshlrev_b32_e32 v20, 3, v3
	v_or_b32_e32 v161, 16, v152
	v_and_b32_e32 v28, 0x70, v2
	v_lshl_add_u64 v[2:3], s[42:43], 0, v[98:99]
	s_mov_b64 s[8:9], 0xac00100
	v_lshl_add_u32 v1, v189, 6, s11
	v_lshlrev_b32_e32 v6, 3, v6
	v_lshlrev_b32_e32 v7, 3, v7
	v_lshlrev_b32_e32 v8, 3, v8
	v_lshlrev_b32_e32 v9, 3, v9
	v_lshlrev_b32_e32 v10, 6, v193
	v_lshlrev_b32_e32 v11, 6, v153
	v_lshlrev_b32_e32 v12, 6, v154
	v_lshlrev_b32_e32 v13, 6, v155
	v_lshl_add_u32 v22, v152, 7, s11
	v_lshl_add_u32 v24, v160, 7, s11
	v_lshl_add_u32 v26, v161, 7, s11
	v_lshl_add_u32 v27, v162, 7, s11
	v_lshl_add_u64 v[132:133], v[2:3], 0, s[8:9]
	s_mov_b64 s[8:9], 0xa008000
	v_and_b32_e32 v149, 24, v220
	v_lshl_add_u64 v[134:135], v[2:3], 0, s[8:9]
	v_add_u32_e32 v163, v1, v6
	v_add_u32_e32 v164, v1, v7
	v_add_u32_e32 v165, v1, v8
	v_add_u32_e32 v166, v1, v9
	v_add_u32_e32 v167, v4, v10
	v_add_u32_e32 v168, v4, v11
	v_add_u32_e32 v169, v4, v12
	v_add_u32_e32 v170, v4, v13
	v_lshlrev_b32_e32 v136, 1, v0
	s_movk_i32 s11, 0x4000
	s_mov_b32 s19, 0x41000000
	s_mov_b64 s[20:21], 0x80
	v_add_u32_e32 v171, v5, v14
	v_add_u32_e32 v172, v5, v15
	v_add_u32_e32 v173, v5, v16
	v_add_u32_e32 v174, v5, v17
	v_add_u32_e32 v175, v5, v18
	v_add_u32_e32 v176, v5, v19
	v_add_u32_e32 v177, v5, v20
	v_add_u32_e32 v178, v5, v21
	v_add_u32_e32 v179, v22, v23
	v_add_u32_e32 v180, v24, v25
	v_add_u32_e32 v181, v26, v23
	v_add_u32_e32 v182, v27, v28
	v_mov_b32_e32 v183, 0x3c3504f3
	v_mov_b32_e32 v184, 0x3c800000
	s_mov_b32 s28, s75
	s_cmp_eq_u32 s98, 0
	s_cbranch_scc1 .LBB0_300
	s_cmp_eq_u32 s98, 2
	s_cbranch_scc1 .Lp23_resume
	s_mov_b32 s44, -1
	s_and_b32 s45, s75, 3
	s_cmp_eq_u32 s98, 1
	s_cbranch_scc1 .LBB0_299
	s_bfe_u32 s45, s75, 0x20002
	s_branch .LBB0_299
.Lp23_resume:
	s_mov_b32 s98, 1
	s_branch .LBB0_299
.Lp3_enter:
	s_barrier
	v_readlane_b32 s70, v254, 7
	v_readlane_b32 s62, v254, 16
	v_readlane_b32 s64, v254, 18
	v_readlane_b32 s76, v254, 24
	v_readlane_b32 s71, v254, 8
	v_readlane_b32 s63, v254, 17
	v_readlane_b32 s65, v254, 19
	v_readlane_b32 s72, v254, 20
	v_readlane_b32 s73, v254, 21
	v_readlane_b32 s77, v254, 25
	s_mov_b64 s[20:21], s[90:91]
	s_mov_b64 s[22:23], s[92:93]
	s_mov_b64 s[26:27], s[94:95]
	v_mbcnt_lo_u32_b32 v218, -1, 0
	v_lshrrev_b32_e32 v219, 1, v191
	v_lshlrev_b32_e32 v220, 3, v191
	v_lshlrev_b32_e32 v0, 2, v190
	s_branch .Lp3_pre

.LBB0_299:
	s_cmp_eq_u32 s98, 0
	s_cbranch_scc1 .Lp3_generic
	s_add_i32 s44, s44, 1
	s_cmp_eq_u32 s98, 3
	s_cbranch_scc1 .Lp23_B
	s_cmp_gt_u32 s44, 3
	s_cbranch_scc1 .Lp23_endA
	s_cmp_eq_u32 s44, s45
	s_cbranch_scc1 .Lp23_burst
	s_mov_b32 s28, s44
	s_cmp_gt_u32 s44, s45
	s_cbranch_scc0 .Lp23_set
	s_add_i32 s28, s28, -1

.Lp23_burst:
	s_barrier
	s_mov_b32 s11, s86
	s_mov_b32 s64, s87
	s_mov_b32 s76, s88
	s_mov_b32 s77, s89
	s_mov_b32 s98, 2
	s_branch .Lp2_entry
.Lp23_endA:
	s_mov_b32 s98, 3
	s_mov_b64 s[20:21], s[90:91]
	s_mov_b64 s[22:23], s[92:93]
	s_mov_b64 s[26:27], s[94:95]
	v_mbcnt_lo_u32_b32 v218, -1, 0
	v_lshrrev_b32_e32 v219, 1, v191
	v_lshlrev_b32_e32 v220, 3, v191
	s_branch .LBB0_244
.Lp23_B:
	s_cmp_gt_u32 s44, 8
	s_cbranch_scc1 .LBB0_320
	s_add_i32 s28, s44, 3
	s_cmp_lt_u32 s44, s45
	s_cbranch_scc1 .Lp23_set
	s_add_i32 s28, s44, 6
	s_sub_u32 s28, s28, s45
	s_cmp_lt_u32 s28, 12
	s_cbranch_scc1 .Lp23_set
	s_add_i32 s28, s44, -3
	s_branch .Lp23_set
